# rwkv prep: 8 more non-adjacent single-value cvt_pk pairs merged into packed cvt + ds_write_b16_d16_hi, on top of v068
# speedup vs baseline: 1.0024x; 1.0024x over previous
.LBB0_637:
	v_cvt_f32_f16_e32 v69, v108
	v_cvt_f32_f16_sdwa v70, v108 dst_sel:DWORD dst_unused:UNUSED_PAD src0_sel:WORD_1
	v_cvt_f32_f16_sdwa v218, v110 dst_sel:DWORD dst_unused:UNUSED_PAD src0_sel:WORD_1
	v_cvt_f32_f16_sdwa v72, v109 dst_sel:DWORD dst_unused:UNUSED_PAD src0_sel:WORD_1
	v_add_f32_e32 v69, 0, v69
	v_mul_f32_e32 v74, 0x3fb8aa3b, v69
	v_exp_f32_e32 v74, v74
	v_mul_f32_e32 v76, v218, v70
	v_add_f32_e32 v70, -1.0, v70
	v_cvt_f32_f16_e32 v73, v110
	v_fma_f32 v70, v151, v70, 1.0
	v_mul_f32_e32 v70, v70, v72
	v_mul_f32_e32 v75, 0xbfb8aa3b, v69
	v_mul_f32_e32 v70, v74, v70
	v_cvt_f32_f16_e32 v71, v109
	v_exp_f32_e32 v75, v75
	v_cvt_pk_bf16_f32 v70, v70, v73
	ds_write_b16 v165, v70
	ds_write_b16_d16_hi v166, v70
	v_cvt_f32_f16_e32 v70, v66
	v_mul_f32_e32 v71, v75, v71
	v_mul_f32_e32 v76, v76, v74
	v_cvt_pk_bf16_f32 v71, v71, s0
	v_cvt_f32_f16_sdwa v66, v66 dst_sel:DWORD dst_unused:UNUSED_PAD src0_sel:WORD_1
	v_cvt_f32_f16_e32 v72, v68
	v_cvt_f32_f16_sdwa v68, v68 dst_sel:DWORD dst_unused:UNUSED_PAD src0_sel:WORD_1
	ds_write_b16 v163, v71
	v_cvt_pk_bf16_f32 v71, v76, s0
	v_add_f32_e32 v69, v69, v70
	ds_write_b16 v164, v71
	v_cvt_f32_f16_e32 v71, v67
	v_cvt_f32_f16_sdwa v67, v67 dst_sel:DWORD dst_unused:UNUSED_PAD src0_sel:WORD_1
	v_mul_f32_e32 v73, 0x3fb8aa3b, v69
	v_exp_f32_e32 v73, v73
	v_mul_f32_e64 v234, v75, -v68
	v_mul_f32_e32 v68, v68, v66
	v_add_f32_e32 v66, -1.0, v66
	v_fma_f32 v66, v151, v66, 1.0
	v_mul_f32_e32 v70, 0xbfb8aa3b, v69
	v_mul_f32_e32 v66, v66, v67
	v_exp_f32_e32 v70, v70
	v_mul_f32_e32 v66, v73, v66
	v_cvt_pk_bf16_f32 v66, v66, v72
	ds_write_b16 v164, v66 offset:2448
	ds_write_b16_d16_hi v166, v66 offset:144
	v_cvt_f32_f16_e32 v66, v63
	v_mul_f32_e32 v67, v70, v71
	v_mul_f32_e32 v68, v68, v73
	v_cvt_pk_bf16_f32 v67, v67, s0
	ds_write_b16 v155, v67 offset:2448
	v_cvt_pk_bf16_f32 v67, v68, v234
	v_cvt_f32_f16_sdwa v63, v63 dst_sel:DWORD dst_unused:UNUSED_PAD src0_sel:WORD_1
	v_cvt_f32_f16_e32 v68, v65
	v_cvt_f32_f16_sdwa v65, v65 dst_sel:DWORD dst_unused:UNUSED_PAD src0_sel:WORD_1
	v_add_f32_e32 v66, v69, v66
	ds_write_b16_d16_hi v155, v67 offset:144
	ds_write_b16 v164, v67 offset:144
	v_cvt_f32_f16_e32 v67, v64
	v_cvt_f32_f16_sdwa v64, v64 dst_sel:DWORD dst_unused:UNUSED_PAD src0_sel:WORD_1
	v_mul_f32_e32 v71, 0x3fb8aa3b, v66
	v_exp_f32_e32 v71, v71
	v_mul_f32_e64 v241, v70, -v65
	v_mul_f32_e32 v65, v65, v63
	v_add_f32_e32 v63, -1.0, v63
	v_fma_f32 v63, v151, v63, 1.0
	v_mul_f32_e32 v69, 0xbfb8aa3b, v66
	v_mul_f32_e32 v63, v63, v64
	v_exp_f32_e32 v69, v69
	v_mul_f32_e32 v63, v63, v71
	v_cvt_pk_bf16_f32 v63, v63, v68
	ds_write_b16 v164, v63 offset:2592
	ds_write_b16_d16_hi v166, v63 offset:288
	v_cvt_f32_f16_e32 v63, v60
	v_mul_f32_e32 v64, v69, v67
	v_mul_f32_e32 v65, v65, v71
	v_cvt_pk_bf16_f32 v64, v64, s0
	ds_write_b16 v155, v64 offset:2592
	v_cvt_pk_bf16_f32 v64, v65, v241
	v_cvt_f32_f16_sdwa v60, v60 dst_sel:DWORD dst_unused:UNUSED_PAD src0_sel:WORD_1
	v_cvt_f32_f16_e32 v65, v62
	v_cvt_f32_f16_sdwa v62, v62 dst_sel:DWORD dst_unused:UNUSED_PAD src0_sel:WORD_1
	v_add_f32_e32 v63, v66, v63
	ds_write_b16_d16_hi v155, v64 offset:288
	ds_write_b16 v164, v64 offset:288
	v_cvt_f32_f16_e32 v64, v61
	v_cvt_f32_f16_sdwa v61, v61 dst_sel:DWORD dst_unused:UNUSED_PAD src0_sel:WORD_1
	v_mul_f32_e32 v67, 0x3fb8aa3b, v63
	v_exp_f32_e32 v67, v67
	v_mul_f32_e64 v235, v69, -v62
	v_mul_f32_e32 v62, v62, v60
	v_add_f32_e32 v60, -1.0, v60
	v_fma_f32 v60, v151, v60, 1.0
	v_mul_f32_e32 v66, 0xbfb8aa3b, v63
	v_mul_f32_e32 v60, v60, v61
	v_exp_f32_e32 v66, v66
	v_mul_f32_e32 v60, v60, v67
	v_cvt_pk_bf16_f32 v60, v60, v65
	ds_write_b16 v164, v60 offset:2736
	ds_write_b16_d16_hi v166, v60 offset:432
	v_cvt_f32_f16_e32 v60, v9
	v_mul_f32_e32 v61, v66, v64
	v_mul_f32_e32 v62, v62, v67
	v_cvt_pk_bf16_f32 v61, v61, s0
	ds_write_b16 v155, v61 offset:2736
	v_cvt_pk_bf16_f32 v61, v62, v235
	v_cvt_f32_f16_sdwa v9, v9 dst_sel:DWORD dst_unused:UNUSED_PAD src0_sel:WORD_1
	v_cvt_f32_f16_e32 v62, v11
	v_cvt_f32_f16_sdwa v11, v11 dst_sel:DWORD dst_unused:UNUSED_PAD src0_sel:WORD_1
	v_add_f32_e32 v60, v63, v60
	ds_write_b16_d16_hi v155, v61 offset:432
	ds_write_b16 v164, v61 offset:432
	v_cvt_f32_f16_e32 v61, v10
	v_cvt_f32_f16_sdwa v10, v10 dst_sel:DWORD dst_unused:UNUSED_PAD src0_sel:WORD_1
	v_mul_f32_e32 v64, 0x3fb8aa3b, v60
	v_exp_f32_e32 v64, v64
	v_mul_f32_e64 v244, v66, -v11
	v_mul_f32_e32 v11, v11, v9
	v_add_f32_e32 v9, -1.0, v9
	v_fma_f32 v9, v151, v9, 1.0
	v_mul_f32_e32 v63, 0xbfb8aa3b, v60
	v_mul_f32_e32 v9, v9, v10
	v_exp_f32_e32 v63, v63
	v_mul_f32_e32 v9, v9, v64
	v_cvt_pk_bf16_f32 v9, v9, v62
	ds_write_b16 v164, v9 offset:2880
	ds_write_b16_d16_hi v166, v9 offset:576
	v_cvt_f32_f16_e32 v9, v6
	v_mul_f32_e32 v10, v63, v61
	v_mul_f32_e32 v11, v11, v64
	v_cvt_pk_bf16_f32 v10, v10, s0
	ds_write_b16 v155, v10 offset:2880
	v_cvt_pk_bf16_f32 v10, v11, v244
	v_cvt_f32_f16_sdwa v6, v6 dst_sel:DWORD dst_unused:UNUSED_PAD src0_sel:WORD_1
	v_cvt_f32_f16_e32 v11, v8
	v_cvt_f32_f16_sdwa v8, v8 dst_sel:DWORD dst_unused:UNUSED_PAD src0_sel:WORD_1
	v_add_f32_e32 v9, v60, v9
	ds_write_b16_d16_hi v155, v10 offset:576
	ds_write_b16 v164, v10 offset:576
	v_cvt_f32_f16_e32 v10, v7
	v_cvt_f32_f16_sdwa v7, v7 dst_sel:DWORD dst_unused:UNUSED_PAD src0_sel:WORD_1
	v_mul_f32_e32 v61, 0x3fb8aa3b, v9
	v_exp_f32_e32 v61, v61
	v_mul_f32_e64 v247, v63, -v8
	v_mul_f32_e32 v8, v8, v6
	v_add_f32_e32 v6, -1.0, v6
	v_fma_f32 v6, v151, v6, 1.0
	v_mul_f32_e32 v60, 0xbfb8aa3b, v9
	v_mul_f32_e32 v6, v6, v7
	v_exp_f32_e32 v60, v60
	v_mul_f32_e32 v6, v6, v61
	v_cvt_pk_bf16_f32 v6, v6, v11
	ds_write_b16 v164, v6 offset:3024
	ds_write_b16_d16_hi v166, v6 offset:720
	v_cvt_f32_f16_e32 v6, v3
	v_mul_f32_e32 v7, v60, v10
	v_mul_f32_e32 v8, v8, v61
	v_cvt_pk_bf16_f32 v7, v7, s0
	ds_write_b16 v155, v7 offset:3024
	v_cvt_pk_bf16_f32 v7, v8, v247
	v_cvt_f32_f16_sdwa v3, v3 dst_sel:DWORD dst_unused:UNUSED_PAD src0_sel:WORD_1
	v_cvt_f32_f16_e32 v8, v5
	v_cvt_f32_f16_sdwa v5, v5 dst_sel:DWORD dst_unused:UNUSED_PAD src0_sel:WORD_1
	v_add_f32_e32 v6, v9, v6
	ds_write_b16_d16_hi v155, v7 offset:720
	ds_write_b16 v164, v7 offset:720
	v_cvt_f32_f16_e32 v7, v4
	v_cvt_f32_f16_sdwa v4, v4 dst_sel:DWORD dst_unused:UNUSED_PAD src0_sel:WORD_1
	v_mul_f32_e32 v10, 0x3fb8aa3b, v6
	v_exp_f32_e32 v10, v10
	v_mul_f32_e64 v249, v60, -v5
	v_mul_f32_e32 v5, v5, v3
	v_add_f32_e32 v3, -1.0, v3
	v_fma_f32 v3, v151, v3, 1.0
	v_mul_f32_e32 v9, 0xbfb8aa3b, v6
	v_mul_f32_e32 v3, v3, v4
	v_exp_f32_e32 v9, v9
	v_mul_f32_e32 v3, v3, v10
	v_cvt_pk_bf16_f32 v3, v3, v8
	ds_write_b16 v164, v3 offset:3168
	ds_write_b16_d16_hi v166, v3 offset:864
	v_cvt_f32_f16_e32 v3, v0
	v_mul_f32_e32 v4, v9, v7
	v_mul_f32_e32 v5, v5, v10
	v_cvt_pk_bf16_f32 v4, v4, s0
	ds_write_b16 v155, v4 offset:3168
	v_cvt_pk_bf16_f32 v4, v5, v249
	v_cvt_f32_f16_sdwa v0, v0 dst_sel:DWORD dst_unused:UNUSED_PAD src0_sel:WORD_1
	v_cvt_f32_f16_e32 v5, v2
	v_cvt_f32_f16_sdwa v2, v2 dst_sel:DWORD dst_unused:UNUSED_PAD src0_sel:WORD_1
	v_add_f32_e32 v3, v6, v3
	ds_write_b16_d16_hi v155, v4 offset:864
	ds_write_b16 v164, v4 offset:864
	v_cvt_f32_f16_e32 v4, v1
	v_cvt_f32_f16_sdwa v1, v1 dst_sel:DWORD dst_unused:UNUSED_PAD src0_sel:WORD_1
	v_mul_f32_e32 v7, 0x3fb8aa3b, v3
	v_exp_f32_e32 v7, v7
	v_mul_f32_e64 v239, v9, -v2
	v_mul_f32_e32 v2, v2, v0
	v_add_f32_e32 v0, -1.0, v0
	v_mul_f32_e32 v6, 0xbfb8aa3b, v3
	v_fma_f32 v0, v151, v0, 1.0
	v_exp_f32_e32 v6, v6
	v_mul_f32_e32 v0, v0, v1
	v_mul_f32_e32 v0, v0, v7
	v_cvt_pk_bf16_f32 v0, v0, s0
	ds_write_b16 v164, v0 offset:3312
	v_cvt_pk_bf16_f32 v0, v5, s0
	v_mul_f32_e32 v1, v6, v4
	ds_write_b16 v166, v0 offset:1008
	s_waitcnt vmcnt(47)
	v_cvt_f32_f16_e32 v0, v59
	v_mul_f32_e32 v2, v2, v7
	v_cvt_pk_bf16_f32 v1, v1, v2
	ds_write_b16 v155, v1 offset:3312
	ds_write_b16_d16_hi v164, v1 offset:1008
	s_waitcnt vmcnt(46)
	v_cvt_f32_f16_e32 v1, v58
	s_waitcnt vmcnt(42)
	v_cvt_f32_f16_e32 v7, v51
	v_cvt_pk_bf16_f32 v4, v239, s0
	v_add_f32_e32 v0, v3, v0
	ds_write_b16 v155, v4 offset:1008
	v_cvt_f32_f16_e32 v4, v53
	v_mul_f32_e32 v8, 0x3fb8aa3b, v0
	v_exp_f32_e32 v8, v8
	v_mul_f32_e64 v242, v6, -v7
	v_mul_f32_e32 v6, v7, v1
	v_add_f32_e32 v1, -1.0, v1
	v_cvt_f32_f16_e32 v5, v57
	v_mul_f32_e32 v3, 0xbfb8aa3b, v0
	v_fma_f32 v1, v151, v1, 1.0
	v_cvt_f32_f16_e32 v2, v55
	v_exp_f32_e32 v3, v3
	v_mul_f32_e32 v1, v1, v4
	v_mul_f32_e32 v1, v1, v8
	v_cvt_pk_bf16_f32 v1, v1, s0
	ds_write_b16 v170, v1
	v_cvt_pk_bf16_f32 v1, v5, s0
	v_mul_f32_e32 v2, v3, v2
	ds_write_b16 v171, v1
	s_waitcnt vmcnt(41)
	v_cvt_f32_f16_e32 v1, v50
	v_mul_f32_e32 v6, v6, v8
	v_cvt_pk_bf16_f32 v2, v2, v6
	ds_write_b16 v168, v2
	ds_write_b16_d16_hi v169, v2
	s_waitcnt vmcnt(40)
	v_cvt_f32_f16_e32 v2, v47
	s_waitcnt vmcnt(36)
	v_cvt_f32_f16_e32 v7, v49
	v_add_f32_e32 v0, v0, v1
	v_cvt_f32_f16_e32 v5, v52
	v_mul_f32_e32 v8, 0x3fb8aa3b, v0
	v_exp_f32_e32 v8, v8
	v_mul_f32_e64 v246, v3, -v7
	v_mul_f32_e32 v3, v7, v2
	v_add_f32_e32 v2, -1.0, v2
	v_cvt_f32_f16_e32 v6, v56
	v_fma_f32 v2, v151, v2, 1.0
	v_mul_f32_e32 v2, v2, v5
	v_mul_f32_e32 v2, v2, v8
	v_cvt_pk_bf16_f32 v2, v2, v6
	ds_write_b16 v164, v2 offset:3600
	ds_write_b16_d16_hi v166, v2 offset:1296
	s_waitcnt vmcnt(35)
	v_cvt_f32_f16_e32 v2, v48
	v_mul_f32_e32 v3, v3, v8
	v_cvt_pk_bf16_f32 v4, v242, s0
	v_mul_f32_e32 v1, 0xbfb8aa3b, v0
	v_cvt_pk_bf16_f32 v3, v3, s0
	ds_write_b16 v167, v4
	v_cvt_f32_f16_e32 v4, v54
	v_exp_f32_e32 v1, v1
	ds_write_b16 v164, v3 offset:1296
	s_waitcnt vmcnt(34)
	v_cvt_f32_f16_e32 v3, v45
	s_waitcnt vmcnt(30)
	v_cvt_f32_f16_e32 v7, v46
	v_add_f32_e32 v0, v0, v2
	v_cvt_pk_bf16_f32 v5, v246, s0
	v_mul_f32_e32 v8, 0x3fb8aa3b, v0
	ds_write_b16 v155, v5 offset:1296
	v_cvt_f32_f16_e32 v5, v44
	v_exp_f32_e32 v8, v8
	v_mul_f32_e32 v4, v1, v4
	v_mul_f32_e64 v248, v1, -v7
	v_mul_f32_e32 v1, v7, v3
	v_add_f32_e32 v3, -1.0, v3
	v_cvt_f32_f16_e32 v6, v43
	v_fma_f32 v3, v151, v3, 1.0
	v_mul_f32_e32 v1, v1, v8
	v_mul_f32_e32 v3, v3, v5
	v_mul_f32_e32 v3, v3, v8
	v_cvt_pk_bf16_f32 v1, v1, v3
	ds_write_b16 v164, v1 offset:1440
	ds_write_b16_d16_hi v164, v1 offset:3744
	v_cvt_pk_bf16_f32 v1, v6, s0
	ds_write_b16 v166, v1 offset:1440
	s_waitcnt vmcnt(29)
	v_cvt_f32_f16_e32 v1, v39
	v_cvt_pk_bf16_f32 v4, v4, s0
	v_mul_f32_e32 v2, 0xbfb8aa3b, v0
	ds_write_b16 v155, v4 offset:3600
	v_cvt_f32_f16_e32 v4, v34
	v_exp_f32_e32 v2, v2
	s_waitcnt vmcnt(28)
	v_cvt_f32_f16_e32 v3, v36
	s_waitcnt vmcnt(24)
	v_cvt_f32_f16_e32 v7, v28
	v_add_f32_e32 v0, v0, v1
	v_cvt_pk_bf16_f32 v5, v248, s0
	v_mul_f32_e32 v8, 0x3fb8aa3b, v0
	ds_write_b16 v155, v5 offset:1440
	v_cvt_f32_f16_e32 v5, v31
	v_exp_f32_e32 v8, v8
	v_mul_f32_e32 v4, v2, v4
	v_mul_f32_e64 v225, v2, -v7
	v_mul_f32_e32 v2, v7, v3
	v_add_f32_e32 v3, -1.0, v3
	v_cvt_f32_f16_e32 v6, v35
	v_fma_f32 v3, v151, v3, 1.0
	v_mul_f32_e32 v2, v2, v8
	v_mul_f32_e32 v3, v3, v5
	v_mul_f32_e32 v3, v3, v8
	v_cvt_pk_bf16_f32 v2, v2, v3
	ds_write_b16 v164, v2 offset:1584
	ds_write_b16_d16_hi v164, v2 offset:3888
	v_cvt_pk_bf16_f32 v2, v6, s0
	ds_write_b16 v166, v2 offset:1584
	s_waitcnt vmcnt(23)
	v_cvt_f32_f16_e32 v2, v42
	v_cvt_pk_bf16_f32 v4, v4, s0
	v_mul_f32_e32 v1, 0xbfb8aa3b, v0
	ds_write_b16 v155, v4 offset:3744
	v_cvt_f32_f16_e32 v4, v32
	v_exp_f32_e32 v1, v1
	s_waitcnt vmcnt(22)
	v_cvt_f32_f16_e32 v3, v41
	s_waitcnt vmcnt(18)
; #define LAS __attribute__((address_space(3)))
; #define MFMA32(a, b, c) __builtin_amdgcn_mfma_f32_32x32x16_bf16((a), (b), (c), 0, 0, 0)
; __device__ __forceinline__ unsigned lds_u16(const LAS bf16* p) { return (unsigned)*p; }
; __device__ __forceinline__ void phase_rwkv_fused(const Frame& F, const Args& a, int l) {
;     ...
; #pragma unroll
;         for (int vt = 0; vt < 2; ++vt) { v4u w;
; #pragma unroll
;             for (int q = 0; q < 4; ++q) w[q] = lds_u16(VL + (8 * hh + 2 * q) * LDA + 32 * vt + li) | (lds_u16(VL + (8 * hh + 2 * q + 1) * LDA + 32 * vt + li) << 16);
;             frv[vt] = w; }
;         f32x16 g;
; #pragma unroll
;         for (int e = 0; e < 16; ++e) g[e] = 0.f;
; #pragma unroll
;         for (int ks = 0; ks < 4; ++ks) { const bf16x8 af = *(const LAS bf16x8*)(AR + li * LDA + 16 * ks + 8 * hh); const bf16x8 bf = *(const LAS bf16x8*)(BK + li * LDA + 16 * ks + 8 * hh); g = MFMA32(af, bf, g); }
	v_cvt_f32_f16_e32 v7, v33
	v_add_f32_e32 v0, v0, v2
	v_cvt_pk_bf16_f32 v5, v225, s0
	v_mul_f32_e32 v8, 0x3fb8aa3b, v0
	ds_write_b16 v155, v5 offset:1584
	v_cvt_f32_f16_e32 v5, v37
	v_exp_f32_e32 v8, v8
	v_mul_f32_e32 v4, v1, v4
	v_mul_f32_e64 v226, v1, -v7
	v_mul_f32_e32 v1, v3, v7
	v_add_f32_e32 v3, -1.0, v3
	v_cvt_f32_f16_e32 v6, v40
	v_fma_f32 v3, v151, v3, 1.0
	v_mul_f32_e32 v1, v1, v8
	v_mul_f32_e32 v3, v3, v5
	v_mul_f32_e32 v3, v3, v8
	v_cvt_pk_bf16_f32 v1, v1, v3
	ds_write_b16 v164, v1 offset:1728
	ds_write_b16_d16_hi v164, v1 offset:4032
	v_cvt_pk_bf16_f32 v1, v6, s0
	ds_write_b16 v166, v1 offset:1728
	s_waitcnt vmcnt(17)
	v_cvt_f32_f16_e32 v1, v23
	v_cvt_pk_bf16_f32 v4, v4, s0
	v_mul_f32_e32 v2, 0xbfb8aa3b, v0
	ds_write_b16 v155, v4 offset:3888
	v_cvt_f32_f16_e32 v4, v38
	v_exp_f32_e32 v2, v2
	s_waitcnt vmcnt(16)
	v_cvt_f32_f16_e32 v3, v29
	s_waitcnt vmcnt(12)
	v_cvt_f32_f16_e32 v7, v30
	v_add_f32_e32 v0, v0, v1
	v_cvt_pk_bf16_f32 v5, v226, s0
	v_mul_f32_e32 v8, 0x3fb8aa3b, v0
	ds_write_b16 v155, v5 offset:1728
	v_cvt_f32_f16_e32 v5, v24
	v_exp_f32_e32 v8, v8
	v_mul_f32_e32 v4, v2, v4
	v_mul_f32_e64 v229, v2, -v7
	v_mul_f32_e32 v2, v3, v7
	v_add_f32_e32 v3, -1.0, v3
	v_cvt_f32_f16_e32 v6, v27
	v_fma_f32 v3, v151, v3, 1.0
	v_mul_f32_e32 v2, v2, v8
	v_mul_f32_e32 v3, v3, v5
	v_mul_f32_e32 v3, v3, v8
	v_cvt_pk_bf16_f32 v2, v2, v3
	ds_write_b16 v164, v2 offset:1872
	ds_write_b16_d16_hi v164, v2 offset:4176
	v_cvt_pk_bf16_f32 v2, v6, s0
	ds_write_b16 v166, v2 offset:1872
	s_waitcnt vmcnt(11)
	v_cvt_f32_f16_e32 v2, v22
	v_cvt_pk_bf16_f32 v4, v4, s0
	v_mul_f32_e32 v1, 0xbfb8aa3b, v0
	ds_write_b16 v155, v4 offset:4032
	v_cvt_f32_f16_e32 v4, v25
	v_exp_f32_e32 v1, v1
	s_waitcnt vmcnt(10)
	v_cvt_f32_f16_e32 v3, v20
	s_waitcnt vmcnt(6)
	v_cvt_f32_f16_e32 v7, v19
	v_add_f32_e32 v0, v0, v2
	v_cvt_pk_bf16_f32 v5, v229, s0
	v_mul_f32_e32 v8, 0x3fb8aa3b, v0
	ds_write_b16 v155, v5 offset:1872
	v_cvt_f32_f16_e32 v5, v15
	v_exp_f32_e32 v8, v8
	v_mul_f32_e32 v4, v1, v4
	v_mul_f32_e64 v231, v1, -v7
	v_mul_f32_e32 v1, v3, v7
	v_add_f32_e32 v3, -1.0, v3
	v_cvt_f32_f16_e32 v6, v26
	v_fma_f32 v3, v151, v3, 1.0
	v_mul_f32_e32 v1, v1, v8
	v_mul_f32_e32 v3, v3, v5
	v_mul_f32_e32 v3, v3, v8
	v_cvt_pk_bf16_f32 v1, v1, v3
	ds_write_b16 v164, v1 offset:2016
	ds_write_b16_d16_hi v164, v1 offset:4320
	v_cvt_pk_bf16_f32 v1, v6, s0
	v_cvt_pk_bf16_f32 v4, v4, s0
	v_mul_f32_e32 v2, 0xbfb8aa3b, v0
	ds_write_b16 v166, v1 offset:2016
	s_waitcnt vmcnt(5)
	v_cvt_f32_f16_e32 v1, v21
	ds_write_b16 v155, v4 offset:4176
	v_cvt_f32_f16_e32 v4, v16
	v_exp_f32_e32 v2, v2
	s_waitcnt vmcnt(4)
	v_cvt_f32_f16_e32 v3, v18
	s_waitcnt vmcnt(0)
	v_cvt_f32_f16_e32 v7, v12
	v_cvt_pk_bf16_f32 v5, v231, s0
	v_add_f32_e32 v0, v0, v1
	v_mul_f32_e32 v4, v2, v4
	ds_write_b16 v155, v5 offset:2016
	v_cvt_f32_f16_e32 v5, v13
	v_mul_f32_e32 v1, 0xbfb8aa3b, v0
	v_mul_f32_e32 v0, 0x3fb8aa3b, v0
	v_cvt_pk_bf16_f32 v4, v4, s0
	v_exp_f32_e32 v0, v0
	ds_write_b16 v155, v4 offset:4320
	v_cvt_f32_f16_e32 v4, v14
	v_exp_f32_e32 v194, v1
	v_mul_f32_e64 v219, v2, -v7
	v_add_f32_e32 v2, -1.0, v3
	v_cvt_f32_f16_e32 v6, v17
	v_fma_f32 v2, v151, v2, 1.0
	v_mul_f32_e32 v1, v3, v7
	v_mul_f32_e32 v2, v2, v5
	v_mul_f32_e32 v1, v1, v0
	v_mul_f32_e32 v0, v2, v0
	v_mul_f32_e32 v2, v194, v4
	v_cvt_pk_bf16_f32 v0, v0, s0
	v_cvt_pk_bf16_f32 v230, -v218, s0
	v_cvt_pk_bf16_f32 v3, v219, v2
	v_cvt_pk_bf16_f32 v1, v1, v6
	ds_write_b16 v164, v0 offset:4464
	ds_write_b16 v155, v230
	ds_write_b16 v155, v3 offset:2160
	ds_write_b16_d16_hi v155, v3 offset:4464
	ds_write_b16 v164, v1 offset:2160
	ds_write_b16_d16_hi v166, v1 offset:2160
	s_waitcnt lgkmcnt(0)
	ds_read_b128 v[0:3], v152
	ds_read_b128 v[4:7], v153
	ds_read_b128 v[16:19], v152 offset:32
	ds_read_b128 v[20:23], v153 offset:32
	s_waitcnt lgkmcnt(2)
	v_mfma_f32_32x32x16_bf16 v[0:15], v[0:3], v[4:7], 0
	v_mov_b32_e32 v220, 0
	v_mov_b32_e32 v221, 0
	s_waitcnt lgkmcnt(0)
	v_mfma_f32_32x32x16_bf16 v[0:15], v[16:19], v[20:23], v[0:15]
	ds_read_b128 v[16:19], v152 offset:64
	ds_read_b128 v[20:23], v153 offset:64
	ds_read_u16 v199, v172
	ds_read_u16 v203, v172 offset:144
	ds_read_u16 v200, v172 offset:288
	ds_read_u16 v211, v172 offset:432
	ds_read_u16 v196, v172 offset:496
	ds_read_u16 v195, v172 offset:352
	ds_read_u16 v198, v172 offset:208
	ds_read_u16 v197, v172 offset:64
	ds_read_b128 v[24:27], v152 offset:96
	ds_read_b128 v[28:31], v153 offset:96
	ds_read_u16 v214, v172 offset:576
	ds_read_u16 v216, v172 offset:720
	ds_read_u16 v215, v172 offset:864
	ds_read_u16 v217, v172 offset:1008
	ds_read_u16 v202, v172 offset:1072
	ds_read_u16 v201, v172 offset:928
	ds_read_u16 v213, v172 offset:784
	ds_read_u16 v212, v172 offset:640
	s_waitcnt lgkmcnt(0)
	s_waitcnt lgkmcnt(14)
	v_mfma_f32_32x32x16_bf16 v[0:15], v[16:19], v[20:23], v[0:15]
	v_add_u32_e32 v16, v154, v173
	s_waitcnt lgkmcnt(8)
; #define LAS __attribute__((address_space(3)))
; #define LDS_WAIT() asm volatile("s_waitcnt lgkmcnt(0)" ::: "memory")
; __device__ __forceinline__ unsigned f2bf(float f) { return cvt_pk_bf16(f, f) & 0xffffu; }
; __device__ __forceinline__ void phase_rwkv_fused(const Frame& F, const Args& a, int l) {
;     ...
;         for (int e = 0; e < 16; ++e) GL[((e & 3) + 8 * (e >> 2) + 4 * hh) * GLD + li] = g[e];
;         LDS_WAIT(); asm volatile("" ::: "memory");
;         float y2[16];
; #pragma unroll
;         for (int t = 0; t < 16; ++t) y2[t] = (L < 16 && L < t) ? GL[t * GLD + 16 + (L & 15)] : 0.f;
; #pragma unroll
;         for (int t = 1; t < 16; ++t) {
;             float cf[16];
; #pragma unroll
;             for (int q = 0; q < 4; ++q) { if (4 * q < t) { const f32x4 c4 = *(const LAS f32x4*)(GL + t * GLD + 4 * q); cf[4 * q] = c4.x; cf[4 * q + 1] = c4.y; cf[4 * q + 2] = c4.z; cf[4 * q + 3] = c4.w; } }
; #pragma unroll
;             for (int s = 0; s < 16; ++s) if (s < t) { atf[t] += cf[s] * atf[s]; y2[t] += cf[s] * y2[s]; }
;         }
; #pragma unroll
;         for (int t = 0; t < 16; ++t) { AR[t * LDA + L] = (bf16)f2bf(atf[t]); if (L < 16) M2[t * M2D + L] = (bf16)f2bf(y2[t]); }
	v_mfma_f32_32x32x16_bf16 v[0:15], v[24:27], v[28:31], v[0:15]
	s_nop 11
	ds_write2_b32 v16, v0, v1 offset1:36
	v_add_u32_e32 v0, v154, v174
	ds_write2_b32 v0, v2, v3 offset1:36
	ds_write_b32 v0, v4 offset:864
	v_add_u32_e32 v0, 0x400, v16
	ds_write2_b32 v0, v5, v6 offset0:68 offset1:104
	v_add_u32_e32 v0, 0x600, v16
	ds_write2_b32 v0, v7, v8 offset0:12 offset1:192
	v_add_u32_e32 v0, 0x800, v16
	ds_write2_b32 v0, v9, v10 offset0:100 offset1:136
	v_add_u32_e32 v0, 0xa00, v16
	ds_write2_b32 v0, v11, v12 offset0:44 offset1:224
	v_add_u32_e32 v0, 0xc00, v16
	ds_write2_b32 v0, v13, v14 offset0:132 offset1:168
	ds_write_b32 v16, v15 offset:3888
	s_waitcnt lgkmcnt(0)
	s_and_saveexec_b64 s[16:17], s[34:35]
	ds_read_b32 v221, v175
	s_or_b64 exec, exec, s[16:17]
	v_mov_b32_e32 v222, 0
	s_mov_b64 s[16:17], exec
	v_readlane_b32 s22, v255, 31
	v_readlane_b32 s23, v255, 32
	s_and_b64 s[22:23], s[16:17], s[22:23]
	s_mov_b64 exec, s[22:23]
	ds_read_b32 v222, v176
	s_or_b64 exec, exec, s[16:17]
	s_mov_b64 s[16:17], exec
	v_readlane_b32 s22, v255, 33
	v_readlane_b32 s23, v255, 34
	s_and_b64 s[22:23], s[16:17], s[22:23]
	s_mov_b64 exec, s[22:23]
	ds_read_b32 v220, v177
	s_or_b64 exec, exec, s[16:17]
	v_mov_b32_e32 v223, 0
	v_mov_b32_e32 v224, 0
	s_mov_b64 s[16:17], exec
	v_readlane_b32 s22, v255, 35
	v_readlane_b32 s23, v255, 36
	s_and_b64 s[22:23], s[16:17], s[22:23]
	s_mov_b64 exec, s[22:23]
	ds_read_b32 v224, v178
	s_or_b64 exec, exec, s[16:17]
	s_mov_b64 s[16:17], exec
	v_readlane_b32 s22, v255, 37
	v_readlane_b32 s23, v255, 38
	s_and_b64 s[22:23], s[16:17], s[22:23]
	s_mov_b64 exec, s[22:23]
	ds_read_b32 v223, v179
	s_or_b64 exec, exec, s[16:17]
	v_mov_b32_e32 v227, 0
	v_mov_b32_e32 v228, 0
	s_and_saveexec_b64 s[16:17], s[44:45]
	ds_read_b32 v228, v180
	s_or_b64 exec, exec, s[16:17]
	s_and_saveexec_b64 s[16:17], s[46:47]
	ds_read_b32 v227, v181
	s_or_b64 exec, exec, s[16:17]
	v_mov_b32_e32 v232, 0
	v_mov_b32_e32 v233, 0
	s_and_saveexec_b64 s[16:17], s[48:49]
	ds_read_b32 v233, v182
	s_or_b64 exec, exec, s[16:17]
	s_and_saveexec_b64 s[16:17], s[50:51]
	ds_read_b32 v232, v183
	s_or_b64 exec, exec, s[16:17]
	v_mov_b32_e32 v236, 0
	v_mov_b32_e32 v237, 0
	s_and_saveexec_b64 s[16:17], s[52:53]
	ds_read_b32 v237, v184
	s_or_b64 exec, exec, s[16:17]
	s_and_saveexec_b64 s[16:17], s[54:55]
	ds_read_b32 v236, v186
	s_or_b64 exec, exec, s[16:17]
	v_mov_b32_e32 v238, 0
	v_mov_b32_e32 v240, 0
	s_and_saveexec_b64 s[16:17], s[56:57]
	ds_read_b32 v240, v188
	s_or_b64 exec, exec, s[16:17]
	s_and_saveexec_b64 s[16:17], s[58:59]
	ds_read_b32 v238, v189
	s_or_b64 exec, exec, s[16:17]
	v_mov_b32_e32 v243, 0
	v_mov_b32_e32 v245, 0
	s_and_saveexec_b64 s[16:17], s[60:61]
	ds_read_b32 v245, v190
	s_or_b64 exec, exec, s[16:17]
	s_and_saveexec_b64 s[16:17], s[62:63]
	ds_read_b32 v243, v191
	s_or_b64 exec, exec, s[16:17]
	v_readlane_b32 s16, v255, 39
	v_mov_b32_e32 v0, s68
	s_nop 0
	v_mov_b32_e32 v1, s16
	v_readlane_b32 s16, v255, 41
	ds_read_b128 v[140:143], v0
	ds_read_b128 v[136:139], v1
	v_mov_b32_e32 v0, s16
	v_readlane_b32 s16, v255, 43
	s_nop 1
	v_mov_b32_e32 v1, s16
	v_readlane_b32 s16, v255, 45
	ds_read_b128 v[132:135], v0
	ds_read_b128 v[128:131], v1
	v_mov_b32_e32 v0, s16
	v_readlane_b32 s16, v255, 47
	s_nop 1
	v_mov_b32_e32 v1, s16
	v_readlane_b32 s16, v255, 49
	ds_read_b128 v[124:127], v0
	ds_read_b128 v[120:123], v1
	v_mov_b32_e32 v0, s16
	v_readlane_b32 s16, v255, 51
	s_nop 1
	v_mov_b32_e32 v1, s16
	ds_read_b128 v[116:119], v0
	ds_read_b128 v[112:115], v1
	v_mov_b32_e32 v0, s26
	v_mov_b32_e32 v1, s27
	ds_read_b128 v[108:111], v0
	ds_read_b128 v[104:107], v1
	v_mov_b32_e32 v0, s28
	v_mov_b32_e32 v1, s29
	ds_read_b128 v[100:103], v0
	ds_read_b128 v[96:99], v1
	v_mov_b32_e32 v0, s30
	v_mov_b32_e32 v1, s31
	ds_read_b128 v[92:95], v0
	ds_read_b128 v[84:87], v1
	v_mov_b32_e32 v0, s6
	v_mov_b32_e32 v1, s7
	ds_read_b128 v[88:91], v0
	ds_read_b128 v[80:83], v1
	v_mov_b32_e32 v0, s8
	v_mov_b32_e32 v1, s9
	ds_read_b128 v[76:79], v0
	ds_read_b128 v[72:75], v1
	v_mov_b32_e32 v0, s10
	v_mov_b32_e32 v1, s11
	ds_read_b128 v[68:71], v0
	ds_read_b128 v[64:67], v1
	v_mov_b32_e32 v0, s12
	v_mov_b32_e32 v1, s13
	ds_read_b128 v[60:63], v0
	ds_read_b128 v[56:59], v1
	v_mov_b32_e32 v0, s14
	v_mov_b32_e32 v1, s15
	ds_read_b128 v[52:55], v0
	ds_read_b128 v[48:51], v1
	v_mov_b32_e32 v0, s64
	v_mov_b32_e32 v1, s65
	ds_read_b128 v[44:47], v0
	ds_read_b128 v[40:43], v1
	v_mov_b32_e32 v0, s66
	v_mov_b32_e32 v1, s67
	ds_read_b128 v[32:35], v0
	ds_read_b128 v[36:39], v1
	v_mov_b32_e32 v0, s18
	v_mov_b32_e32 v1, s19
	ds_read_b128 v[28:31], v0
	ds_read_b128 v[24:27], v1
	v_mov_b32_e32 v0, s70
	v_mov_b32_e32 v1, s71
	ds_read_b128 v[20:23], v0
	ds_read_b128 v[16:19], v1
	v_mov_b32_e32 v0, s86
	v_mov_b32_e32 v1, s87
	ds_read_b128 v[12:15], v0
	ds_read_b128 v[8:11], v1
	v_mov_b32_e32 v0, s20
	v_mov_b32_e32 v1, s21
	ds_read_b128 v[4:7], v0
	ds_read_b128 v[0:3], v1
	s_waitcnt lgkmcnt(14)
	v_fma_f32 v63, -v140, v218, v234
	s_waitcnt lgkmcnt(0)
	v_fma_f32 v3, -v136, v218, v241
	v_fmac_f32_e32 v3, v137, v63
	ds_write_b16 v155, v230
	s_and_saveexec_b64 s[16:17], s[4:5]
	s_xor_b64 s[16:17], exec, s[16:17]
	s_cbranch_execz .LBB0_669
	v_cvt_pk_bf16_f32 v18, v63, v3
	ds_write_b16 v155, v18 offset:144
	ds_write_b16_d16_hi v155, v18 offset:288
